# v43: v42 + layer-0 FFN pre-norm phase write-through with flat barrier
# baseline (speedup 1.0000x reference)
.LBB0_1347:
	s_cmp_lt_i32 s59, 11
	s_barrier
	s_cbranch_scc1 .LBB0_1401
	s_waitcnt vmcnt(0)
	s_barrier
	s_and_saveexec_b64 s[2:3], s[0:1]
	s_cbranch_execz .LBB0_1400
	s_waitcnt vmcnt(0) lgkmcnt(0)
	v_mov_b32_e32 v241, 0
	v_lshlrev_b32_e64 v254, 8, s31
	v_mov_b32_e32 v247, 1
	v_mov_b32_e32 v246, 0x3600
	global_atomic_add v248, v246, v247, s[60:61] sc0
	buffer_inv sc1
